# sweep 2 far tiles: also PV(keys 32-63) reads all 16 V operands up front (spare VGPRs), one counted wait per 4 MFMAs
# baseline (speedup 1.0000x reference)
; #define SBAR() __builtin_amdgcn_sched_barrier(0)
; template <bool DIFF> ...
;     ...
;       qkt<DIFF>(a0, b0, K_lds, Q_lds, r32, r32, hi);
;       qkt<DIFF>(a1, b1, K_lds, Q_lds, r32 + 32, r32, hi);
;       SBAR();
;     ...
;       BIAS_APPLY(t, 0, a0, b0, cb0);
;       { const float x1 = fmaf(cb0, C, e1), x2 = fmaf(cb0, C, e2);
; #pragma unroll
;       for (int r = 0; r < 16; ++r) a0[r] = __builtin_amdgcn_exp2f(fmaf(a0[r], C, x1));
;       if (DIFF) {
; #pragma unroll
;         for (int r = 0; r < 16; ++r) a0[r] = fmaf(nsg, __builtin_amdgcn_exp2f(fmaf(b0[r], C, x2)), a0[r]);
;       } }
;       PK4(a0, 0, pa0); PK4(a0, 8, pa1);
.Lsw2f:
	ds_read_b128 v[64:67], v176
	ds_read_b128 v[68:71], v172 offset:36864
	ds_read_b128 v[72:75], v177
	ds_read_b128 v[76:79], v176 offset:8192
	s_waitcnt lgkmcnt(2)
	v_mfma_f32_32x32x16_bf16 v[112:127], v[64:67], v[68:71], 0
	ds_read_b128 v[64:67], v171 offset:36864
	ds_read_b128 v[128:131], v177 offset:8192
	s_waitcnt lgkmcnt(1)
	v_mfma_f32_32x32x16_bf16 v[96:111], v[72:75], v[64:67], 0
	ds_read_b128 v[72:75], v178
	ds_read_b128 v[132:135], v170 offset:36864
	ds_read_b128 v[80:83], v179
	ds_read_b128 v[136:139], v178 offset:8192
	ds_read_b128 v[140:143], v169 offset:36864
	ds_read_b128 v[192:195], v179 offset:8192
	s_waitcnt lgkmcnt(1)
	v_mfma_f32_32x32x16_bf16 v[96:111], v[80:83], v[140:143], v[96:111]
	v_mfma_f32_32x32x16_bf16 v[112:127], v[72:75], v[132:135], v[112:127]
	ds_read_b128 v[72:75], v180
	ds_read_b128 v[196:199], v168 offset:36864
	ds_read_b128 v[80:83], v181
	ds_read_b128 v[200:203], v180 offset:8192
	ds_read_b128 v[204:207], v167 offset:36864
	ds_read_b128 v[210:213], v181 offset:8192
	s_waitcnt lgkmcnt(1)
	v_mfma_f32_32x32x16_bf16 v[96:111], v[80:83], v[204:207], v[96:111]
	v_mfma_f32_32x32x16_bf16 v[112:127], v[72:75], v[196:199], v[112:127]
	ds_read_b128 v[72:75], v182
	ds_read_b128 v[214:217], v166 offset:36864
	ds_read_b128 v[80:83], v183
	ds_read_b128 v[218:221], v182 offset:8192
	ds_read_b128 v[222:225], v149 offset:36864
	ds_read_b128 v[226:229], v183 offset:8192
	s_waitcnt lgkmcnt(1)
	v_mfma_f32_32x32x16_bf16 v[96:111], v[80:83], v[222:225], v[96:111]
	v_mfma_f32_32x32x16_bf16 v[112:127], v[72:75], v[214:217], v[112:127]
	s_waitcnt lgkmcnt(0)
	v_mfma_f32_32x32x16_bf16 v[80:95], v[76:79], v[68:71], 0
	v_fmamk_f32 v235, v234, 0x3e38aa3b, v188
	v_fmamk_f32 v234, v234, 0x3e38aa3b, v187
	s_nop 8
	v_fmamk_f32 v112, v112, 0x3e38aa3b, v235
	v_fmamk_f32 v113, v113, 0x3e38aa3b, v235
	v_fmamk_f32 v114, v114, 0x3e38aa3b, v235
	v_fmamk_f32 v115, v115, 0x3e38aa3b, v235
	v_fmamk_f32 v116, v116, 0x3e38aa3b, v235
	v_fmamk_f32 v117, v117, 0x3e38aa3b, v235
	v_fmamk_f32 v96, v96, 0x3e38aa3b, v234
	v_fmamk_f32 v97, v97, 0x3e38aa3b, v234
	v_fmamk_f32 v98, v98, 0x3e38aa3b, v234
	v_fmamk_f32 v99, v99, 0x3e38aa3b, v234
	v_fmamk_f32 v100, v100, 0x3e38aa3b, v234
	v_fmamk_f32 v101, v101, 0x3e38aa3b, v234
	v_exp_f32_e32 v112, v112
	v_mfma_f32_32x32x16_bf16 v[64:79], v[128:131], v[64:67], 0
	v_exp_f32_e32 v113, v113
	v_exp_f32_e32 v114, v114
	v_exp_f32_e32 v115, v115
	v_exp_f32_e32 v116, v116
	v_exp_f32_e32 v117, v117
	v_fmamk_f32 v118, v118, 0x3e38aa3b, v235
	v_fmamk_f32 v119, v119, 0x3e38aa3b, v235
	v_fmamk_f32 v120, v120, 0x3e38aa3b, v235
	v_fmamk_f32 v121, v121, 0x3e38aa3b, v235
	v_fmamk_f32 v122, v122, 0x3e38aa3b, v235
	v_mfma_f32_32x32x16_bf16 v[80:95], v[136:139], v[132:135], v[80:95]
	v_fmamk_f32 v123, v123, 0x3e38aa3b, v235
	v_fmamk_f32 v124, v124, 0x3e38aa3b, v235
	v_fmamk_f32 v125, v125, 0x3e38aa3b, v235
	v_fmamk_f32 v126, v126, 0x3e38aa3b, v235
	v_fmac_f32_e32 v235, 0x3e38aa3b, v127
	v_exp_f32_e32 v96, v96
	v_exp_f32_e32 v97, v97
	v_exp_f32_e32 v98, v98
	v_exp_f32_e32 v99, v99
	v_exp_f32_e32 v100, v100
	v_exp_f32_e32 v101, v101
	v_mfma_f32_32x32x16_bf16 v[64:79], v[192:195], v[140:143], v[64:79]
	v_lshl_add_u64 v[128:129], v[150:151], 0, s[34:35]
	v_add_co_u32_e32 v130, vcc, s70, v128
	s_nop 1
	v_addc_co_u32_e32 v131, vcc, 0, v129, vcc
	v_add_co_u32_e32 v132, vcc, s71, v128
	v_lshl_add_u64 v[136:137], v[152:153], 0, s[34:35]
	s_nop 0
	v_addc_co_u32_e32 v133, vcc, 0, v129, vcc
	v_add_co_u32_e32 v138, vcc, s72, v136
	s_nop 1
	v_addc_co_u32_e32 v139, vcc, 0, v137, vcc
	v_add_co_u32_e32 v140, vcc, s73, v136
	global_load_dwordx4 v[128:131], v[130:131], off
	s_nop 0
	global_load_dwordx4 v[132:135], v[132:133], off
	v_addc_co_u32_e32 v141, vcc, 0, v137, vcc
	global_load_dwordx4 v[136:139], v[138:139], off
	s_nop 0
	global_load_dwordx4 v[140:143], v[140:141], off
	v_fmamk_f32 v102, v102, 0x3e38aa3b, v234
	v_fmamk_f32 v103, v103, 0x3e38aa3b, v234
	v_fmamk_f32 v104, v104, 0x3e38aa3b, v234
	v_fmamk_f32 v105, v105, 0x3e38aa3b, v234
	v_fmamk_f32 v106, v106, 0x3e38aa3b, v234
	v_fmamk_f32 v107, v107, 0x3e38aa3b, v234
	v_fmamk_f32 v108, v108, 0x3e38aa3b, v234
	v_fmamk_f32 v109, v109, 0x3e38aa3b, v234
	v_fmamk_f32 v110, v110, 0x3e38aa3b, v234
	v_fmac_f32_e32 v234, 0x3e38aa3b, v111
	v_exp_f32_e32 v118, v118
	v_exp_f32_e32 v119, v119
	v_exp_f32_e32 v120, v120
	v_mfma_f32_32x32x16_bf16 v[80:95], v[200:203], v[196:199], v[80:95]
	v_exp_f32_e32 v121, v121
	v_exp_f32_e32 v122, v122
	v_exp_f32_e32 v123, v123
	v_exp_f32_e32 v124, v124
	v_exp_f32_e32 v125, v125
	v_exp_f32_e32 v126, v126
	v_exp_f32_e32 v127, v235
	v_exp_f32_e32 v102, v102
	v_mfma_f32_32x32x16_bf16 v[64:79], v[210:213], v[204:207], v[64:79]
	v_exp_f32_e32 v103, v103
	v_exp_f32_e32 v104, v104
	v_exp_f32_e32 v105, v105
	v_exp_f32_e32 v106, v106
	v_exp_f32_e32 v107, v107
	v_exp_f32_e32 v108, v108
	v_exp_f32_e32 v109, v109
	v_exp_f32_e32 v110, v110
	v_mfma_f32_32x32x16_bf16 v[80:95], v[218:221], v[214:217], v[80:95]
	v_exp_f32_e32 v111, v234
	v_pk_fma_f32 v[96:97], v[144:145], v[96:97], v[112:113]
	v_pk_fma_f32 v[98:99], v[144:145], v[98:99], v[114:115]
	v_pk_fma_f32 v[100:101], v[144:145], v[100:101], v[116:117]
	v_pk_fma_f32 v[102:103], v[144:145], v[102:103], v[118:119]
	v_pk_fma_f32 v[104:105], v[144:145], v[104:105], v[120:121]
	v_pk_fma_f32 v[106:107], v[144:145], v[106:107], v[122:123]
	v_pk_fma_f32 v[108:109], v[144:145], v[108:109], v[124:125]
	v_mfma_f32_32x32x16_bf16 v[64:79], v[226:229], v[222:225], v[64:79]
	v_pk_fma_f32 v[110:111], v[144:145], v[110:111], v[126:127]
	v_cvt_pk_bf16_f32 v96, v96, v97
	v_cvt_pk_bf16_f32 v97, v98, v99
	v_cvt_pk_bf16_f32 v98, v100, v101
; #define SBAR() __builtin_amdgcn_sched_barrier(0)
; template <int KS> __device__ __forceinline__ void pv_step(f32x16* o, int vb, bf16x8 pa) {
;   const s16x4 l0 = tr_read<v_rd_off(0, KS, 0)>(vb), h0 = tr_read<v_rd_off(0, KS, 1)>(vb), l1 = tr_read<v_rd_off(1, KS, 0)>(vb), h1 = tr_read<v_rd_off(1, KS, 1)>(vb);
;   const s16x4 l2 = tr_read<v_rd_off(2, KS, 0)>(vb), h2 = tr_read<v_rd_off(2, KS, 1)>(vb), l3 = tr_read<v_rd_off(3, KS, 0)>(vb), h3 = tr_read<v_rd_off(3, KS, 1)>(vb);
;   asm volatile("s_waitcnt lgkmcnt(0)" ::: "memory"); SBAR();
;     ...
;   o[0] = __builtin_amdgcn_mfma_f32_32x32x16_bf16(pa, PK(l0, h0), o[0], 0, 0, 0);
;   o[1] = __builtin_amdgcn_mfma_f32_32x32x16_bf16(pa, PK(l1, h1), o[1], 0, 0, 0);
;   o[2] = __builtin_amdgcn_mfma_f32_32x32x16_bf16(pa, PK(l2, h2), o[2], 0, 0, 0);
;   o[3] = __builtin_amdgcn_mfma_f32_32x32x16_bf16(pa, PK(l3, h3), o[3], 0, 0, 0);
;     ...
; }
; template <bool DIFF> ...
;     ...
;       PK4(a0, 0, pa0); PK4(a0, 8, pa1);
;       SBAR();
;       pv_step<0>(o, vb0, pa0); pv_step<1>(o, vb0, pa1);
;       SBAR();
;       BIAS_APPLY(t, 1, a1, b1, cb1);
;       { const float x1 = fmaf(cb1, C, e1), x2 = fmaf(cb1, C, e2);
; #pragma unroll
;       for (int r = 0; r < 16; ++r) a1[r] = __builtin_amdgcn_exp2f(fmaf(a1[r], C, x1));
;       if (DIFF) {
; #pragma unroll
;         for (int r = 0; r < 16; ++r) a1[r] = fmaf(nsg, __builtin_amdgcn_exp2f(fmaf(b1[r], C, x2)), a1[r]);
;       } }
;       PK4(a1, 0, pa2); PK4(a1, 8, pa3);
;       SBAR();
;       pv_step<2>(o, vb0, pa2); pv_step<3>(o, vb0, pa3);
	v_cvt_pk_bf16_f32 v99, v102, v103
	s_nop 0
	v_permlane32_swap_b32_e32 v96, v98
	v_cvt_pk_bf16_f32 v100, v104, v105
	v_cvt_pk_bf16_f32 v101, v106, v107
	v_cvt_pk_bf16_f32 v102, v108, v109
	v_cvt_pk_bf16_f32 v103, v110, v111
	v_permlane32_swap_b32_e32 v97, v99
	v_permlane32_swap_b32_e32 v100, v102
	v_permlane32_swap_b32_e32 v101, v103
	ds_read_b64_tr_b16 v[104:105], v146 offset:0
	ds_read_b64_tr_b16 v[106:107], v146 offset:0x800
	ds_read_b64_tr_b16 v[108:109], v146 offset:0x200
	ds_read_b64_tr_b16 v[110:111], v146 offset:0xa00
	ds_read_b64_tr_b16 v[112:113], v146 offset:0x400
	ds_read_b64_tr_b16 v[114:115], v146 offset:0xc00
	ds_read_b64_tr_b16 v[116:117], v146 offset:0x600
	ds_read_b64_tr_b16 v[118:119], v146 offset:0xe00
	ds_read_b64_tr_b16 v[238:239], v146 offset:0x1000
	ds_read_b64_tr_b16 v[240:241], v146 offset:0x1800
	ds_read_b64_tr_b16 v[242:243], v146 offset:0x1200
	ds_read_b64_tr_b16 v[244:245], v146 offset:0x1a00
	ds_read_b64_tr_b16 v[246:247], v146 offset:0x1400
	ds_read_b64_tr_b16 v[248:249], v146 offset:0x1c00
	ds_read_b64_tr_b16 v[120:121], v146 offset:0x1600
	ds_read_b64_tr_b16 v[122:123], v146 offset:0x1e00
	v_fmamk_f32 v237, v236, 0x3e38aa3b, v188
	v_fmamk_f32 v236, v236, 0x3e38aa3b, v187
	v_fmamk_f32 v80, v80, 0x3e38aa3b, v237
	v_fmamk_f32 v81, v81, 0x3e38aa3b, v237
	v_fmamk_f32 v82, v82, 0x3e38aa3b, v237
	v_fmamk_f32 v83, v83, 0x3e38aa3b, v237
	v_fmamk_f32 v84, v84, 0x3e38aa3b, v237
	v_fmamk_f32 v85, v85, 0x3e38aa3b, v237
	v_fmamk_f32 v86, v86, 0x3e38aa3b, v237
	v_fmamk_f32 v87, v87, 0x3e38aa3b, v237
	s_waitcnt lgkmcnt(0)
	v_mfma_f32_32x32x16_bf16 v[0:15], v[96:99], v[104:107], v[0:15]
	v_fmamk_f32 v88, v88, 0x3e38aa3b, v237
	v_fmamk_f32 v89, v89, 0x3e38aa3b, v237
	v_fmamk_f32 v90, v90, 0x3e38aa3b, v237
	v_fmamk_f32 v91, v91, 0x3e38aa3b, v237
	v_fmamk_f32 v92, v92, 0x3e38aa3b, v237
	v_fmamk_f32 v93, v93, 0x3e38aa3b, v237
	v_fmamk_f32 v94, v94, 0x3e38aa3b, v237
	v_fmac_f32_e32 v237, 0x3e38aa3b, v95
	v_fmamk_f32 v64, v64, 0x3e38aa3b, v236
	v_fmamk_f32 v65, v65, 0x3e38aa3b, v236
	v_fmamk_f32 v66, v66, 0x3e38aa3b, v236
	v_fmamk_f32 v67, v67, 0x3e38aa3b, v236
	v_fmamk_f32 v68, v68, 0x3e38aa3b, v236
	v_fmamk_f32 v69, v69, 0x3e38aa3b, v236
	v_fmamk_f32 v70, v70, 0x3e38aa3b, v236
	v_mfma_f32_32x32x16_bf16 v[16:31], v[96:99], v[108:111], v[16:31]
	v_fmamk_f32 v71, v71, 0x3e38aa3b, v236
	v_fmamk_f32 v72, v72, 0x3e38aa3b, v236
	v_fmamk_f32 v73, v73, 0x3e38aa3b, v236
	v_fmamk_f32 v74, v74, 0x3e38aa3b, v236
	v_fmamk_f32 v75, v75, 0x3e38aa3b, v236
	v_fmamk_f32 v76, v76, 0x3e38aa3b, v236
	v_fmamk_f32 v77, v77, 0x3e38aa3b, v236
	v_fmamk_f32 v78, v78, 0x3e38aa3b, v236
	v_fmac_f32_e32 v236, 0x3e38aa3b, v79
	v_exp_f32_e32 v80, v80
	v_exp_f32_e32 v81, v81
	v_exp_f32_e32 v82, v82
	v_mfma_f32_32x32x16_bf16 v[32:47], v[96:99], v[112:115], v[32:47]
	v_exp_f32_e32 v83, v83
	v_exp_f32_e32 v84, v84
	v_exp_f32_e32 v85, v85
	v_exp_f32_e32 v86, v86
	v_exp_f32_e32 v87, v87
	v_exp_f32_e32 v88, v88
	v_exp_f32_e32 v89, v89
	v_mfma_f32_32x32x16_bf16 v[48:63], v[96:99], v[116:119], v[48:63]
	v_exp_f32_e32 v90, v90
	v_exp_f32_e32 v91, v91
	v_exp_f32_e32 v92, v92
	v_exp_f32_e32 v93, v93
	v_exp_f32_e32 v94, v94
	v_exp_f32_e32 v95, v237
	v_exp_f32_e32 v64, v64
	v_mfma_f32_32x32x16_bf16 v[0:15], v[100:103], v[238:241], v[0:15]
	v_exp_f32_e32 v65, v65
	v_exp_f32_e32 v66, v66
	v_exp_f32_e32 v67, v67
	v_exp_f32_e32 v68, v68
	v_exp_f32_e32 v69, v69
	v_exp_f32_e32 v70, v70
	v_exp_f32_e32 v71, v71
	v_mfma_f32_32x32x16_bf16 v[16:31], v[100:103], v[242:245], v[16:31]
	v_exp_f32_e32 v72, v72
	v_exp_f32_e32 v73, v73
	v_exp_f32_e32 v74, v74
	v_exp_f32_e32 v75, v75
	v_exp_f32_e32 v76, v76
	v_exp_f32_e32 v77, v77
	v_exp_f32_e32 v78, v78
	v_mfma_f32_32x32x16_bf16 v[32:47], v[100:103], v[246:249], v[32:47]
	v_exp_f32_e32 v79, v236
	v_pk_fma_f32 v[64:65], v[144:145], v[64:65], v[80:81]
	v_pk_fma_f32 v[66:67], v[144:145], v[66:67], v[82:83]
	v_pk_fma_f32 v[68:69], v[144:145], v[68:69], v[84:85]
	v_pk_fma_f32 v[70:71], v[144:145], v[70:71], v[86:87]
	v_pk_fma_f32 v[72:73], v[144:145], v[72:73], v[88:89]
	v_pk_fma_f32 v[74:75], v[144:145], v[74:75], v[90:91]
	v_mfma_f32_32x32x16_bf16 v[48:63], v[100:103], v[120:123], v[48:63]
	v_pk_fma_f32 v[76:77], v[144:145], v[76:77], v[92:93]
	v_pk_fma_f32 v[78:79], v[144:145], v[78:79], v[94:95]
	v_cvt_pk_bf16_f32 v64, v64, v65
	v_cvt_pk_bf16_f32 v65, v66, v67
	v_cvt_pk_bf16_f32 v66, v68, v69
	v_cvt_pk_bf16_f32 v67, v70, v71
	v_cvt_pk_bf16_f32 v68, v72, v73
	v_cvt_pk_bf16_f32 v69, v74, v75
	v_cvt_pk_bf16_f32 v70, v76, v77
	v_cvt_pk_bf16_f32 v71, v78, v79
	v_permlane32_swap_b32_e32 v64, v66
	v_permlane32_swap_b32_e32 v65, v67
	v_permlane32_swap_b32_e32 v68, v70
	v_permlane32_swap_b32_e32 v69, v71
	ds_read_b64_tr_b16 v[72:73], v146 offset:0x2000
	ds_read_b64_tr_b16 v[74:75], v146 offset:0x2800
	ds_read_b64_tr_b16 v[76:77], v146 offset:0x2200
	ds_read_b64_tr_b16 v[78:79], v146 offset:0x2a00
	ds_read_b64_tr_b16 v[80:81], v146 offset:0x2400
	ds_read_b64_tr_b16 v[82:83], v146 offset:0x2c00
	ds_read_b64_tr_b16 v[84:85], v146 offset:0x2600
	ds_read_b64_tr_b16 v[86:87], v146 offset:0x2e00
	ds_read_b64_tr_b16 v[238:239], v146 offset:0x3000
	ds_read_b64_tr_b16 v[240:241], v146 offset:0x3800
	ds_read_b64_tr_b16 v[242:243], v146 offset:0x3200
	ds_read_b64_tr_b16 v[244:245], v146 offset:0x3a00
	ds_read_b64_tr_b16 v[246:247], v146 offset:0x3400
	ds_read_b64_tr_b16 v[248:249], v146 offset:0x3c00
	ds_read_b64_tr_b16 v[88:89], v146 offset:0x3600
	ds_read_b64_tr_b16 v[90:91], v146 offset:0x3e00
	s_waitcnt lgkmcnt(8)
	v_mfma_f32_32x32x16_bf16 v[0:15], v[64:67], v[72:75], v[0:15]
	v_mfma_f32_32x32x16_bf16 v[16:31], v[64:67], v[76:79], v[16:31]
	v_mfma_f32_32x32x16_bf16 v[32:47], v[64:67], v[80:83], v[32:47]
	v_mfma_f32_32x32x16_bf16 v[48:63], v[64:67], v[84:87], v[48:63]
	s_waitcnt lgkmcnt(0)
	v_mfma_f32_32x32x16_bf16 v[0:15], v[68:71], v[238:241], v[0:15]
	s_add_u32 s34, s34, 0x20000
	s_addc_u32 s35, s35, 0
	v_add_u32_e32 v173, 64, v173
	s_add_i32 s93, s93, 64
	s_cmp_eq_u32 s2, s34
	v_mfma_f32_32x32x16_bf16 v[16:31], v[68:71], v[242:245], v[16:31]
	v_mfma_f32_32x32x16_bf16 v[32:47], v[68:71], v[246:249], v[32:47]
	v_mfma_f32_32x32x16_bf16 v[48:63], v[68:71], v[88:91], v[48:63]
	s_cbranch_scc1 .LBB0_326
	s_branch .LBB0_310
